# attention Y: cross-half max exchange only on the rare rescale path (all-lanes test on the half-row max is equivalent)
# speedup vs baseline: 1.0008x; 1.0008x over previous
; __device__ __forceinline__ void partialSM(f32x16& p0, f32x16& p1, float& mhat, f32x16& negm, float& alpha, const bool first) {
;     constexpr float THRL = THR * 1.4426950408889634f;
;     float pmax = p0[0];
; #pragma unroll
;     for (int r = 1; r < 16; ++r) pmax = fmaxf(pmax, p0[r]);
; #pragma unroll
;     for (int r = 0; r < 16; ++r) pmax = fmaxf(pmax, p1[r]);
;     { auto rr = __builtin_amdgcn_permlane32_swap(__float_as_uint(pmax), __float_as_uint(pmax), false, false);
;       pmax = fmaxf(__uint_as_float(rr[0]), __uint_as_float(rr[1])); }
;     if (__builtin_expect(!first && __all(pmax <= THRL), 1)) { alpha = 1.f; }
.LBB0_593:
	v_max_f32_e32 v0, v128, v129
	v_max3_f32 v0, v0, v130, v131
	v_max3_f32 v0, v0, v132, v133
	v_max3_f32 v0, v0, v134, v135
	v_max3_f32 v0, v0, v136, v137
	v_max3_f32 v0, v0, v138, v139
	v_max3_f32 v0, v0, v140, v141
	v_max3_f32 v0, v0, v142, v143
	v_max3_f32 v0, v0, v112, v113
	v_max3_f32 v0, v0, v114, v115
	v_max3_f32 v0, v0, v116, v117
	v_max3_f32 v0, v0, v118, v119
	v_max3_f32 v0, v0, v120, v121
	v_max3_f32 v0, v0, v122, v123
	v_max3_f32 v0, v0, v124, v125
	v_max3_f32 v0, v0, v126, v127
	v_cmp_ge_f32_e32 vcc, s24, v0
	s_cmp_eq_u64 vcc, exec
	s_cbranch_scc0 .LBB0_606
	v_mov_b32_e32 v0, 1.0
	s_branch .LBB0_598

; __device__ __forceinline__ void partialSM(f32x16& p0, f32x16& p1, float& mhat, f32x16& negm, float& alpha, const bool first) {
;     constexpr float THRL = THR * 1.4426950408889634f;
;     float pmax = p0[0];
; #pragma unroll
;     for (int r = 1; r < 16; ++r) pmax = fmaxf(pmax, p0[r]);
; #pragma unroll
;     for (int r = 0; r < 16; ++r) pmax = fmaxf(pmax, p1[r]);
;     { auto rr = __builtin_amdgcn_permlane32_swap(__float_as_uint(pmax), __float_as_uint(pmax), false, false);
;       pmax = fmaxf(__uint_as_float(rr[0]), __uint_as_float(rr[1])); }
;     if (__builtin_expect(!first && __all(pmax <= THRL), 1)) { alpha = 1.f; }
.LBB0_602:
	v_max_f32_e32 v2, v128, v129
	v_max3_f32 v2, v2, v130, v131
	v_max3_f32 v2, v2, v132, v133
	v_max3_f32 v2, v2, v134, v135
	v_max3_f32 v2, v2, v136, v137
	v_max3_f32 v2, v2, v138, v139
	v_max3_f32 v2, v2, v140, v141
	v_max3_f32 v2, v2, v142, v143
	v_max3_f32 v2, v2, v112, v113
	v_max3_f32 v2, v2, v114, v115
	v_max3_f32 v2, v2, v116, v117
	v_max3_f32 v2, v2, v118, v119
	v_max3_f32 v2, v2, v120, v121
	v_max3_f32 v2, v2, v122, v123
	v_max3_f32 v2, v2, v124, v125
	v_max3_f32 v2, v2, v126, v127
	v_mov_b32_e32 v3, v2
	v_cmp_ge_f32_e32 vcc, s24, v2
	s_cmp_eq_u64 vcc, exec
	v_mov_b32_e32 v2, 1.0
	s_cbranch_scc0 .LBB0_607
	s_branch .LBB0_590

; __device__ __forceinline__ void partialSM(f32x16& p0, f32x16& p1, float& mhat, f32x16& negm, float& alpha, const bool first) {
;     ...
;     { auto rr = __builtin_amdgcn_permlane32_swap(__float_as_uint(pmax), __float_as_uint(pmax), false, false);
;       pmax = fmaxf(__uint_as_float(rr[0]), __uint_as_float(rr[1])); }
;     if (__builtin_expect(!first && __all(pmax <= THRL), 1)) { alpha = 1.f; }
;     else { const float dl = first ? pmax : fmaxf(pmax, 0.f); mhat += dl; alpha = first ? 0.f : __builtin_amdgcn_exp2f(-dl);
; #pragma unroll
;         for (int r = 0; r < 16; ++r) { p0[r] -= dl; p1[r] -= dl; }
; #pragma unroll
;         for (int r = 0; r < 16; ++r) negm[r] = -mhat; }
.LBB0_606:
	v_mov_b32_e32 v2, v0
	s_nop 1
	v_permlane32_swap_b32_e32 v0, v2
	v_max_f32_e32 v0, v0, v2
	v_max_f32_e32 v0, v0, v0
	v_max_f32_e32 v2, 0, v0
	v_exp_f32_e64 v0, -v2
	v_add_f32_e32 v215, v215, v2
	v_xor_b32_e32 v80, 0x80000000, v215
	v_pk_add_f32 v[128:129], v[128:129], v[2:3] op_sel_hi:[1,0] neg_lo:[0,1] neg_hi:[0,1]
	v_pk_add_f32 v[130:131], v[130:131], v[2:3] op_sel_hi:[1,0] neg_lo:[0,1] neg_hi:[0,1]
	v_pk_add_f32 v[132:133], v[132:133], v[2:3] op_sel_hi:[1,0] neg_lo:[0,1] neg_hi:[0,1]
	v_pk_add_f32 v[134:135], v[134:135], v[2:3] op_sel_hi:[1,0] neg_lo:[0,1] neg_hi:[0,1]
	v_pk_add_f32 v[136:137], v[136:137], v[2:3] op_sel_hi:[1,0] neg_lo:[0,1] neg_hi:[0,1]
	v_pk_add_f32 v[138:139], v[138:139], v[2:3] op_sel_hi:[1,0] neg_lo:[0,1] neg_hi:[0,1]
	v_pk_add_f32 v[140:141], v[140:141], v[2:3] op_sel_hi:[1,0] neg_lo:[0,1] neg_hi:[0,1]
	v_pk_add_f32 v[142:143], v[142:143], v[2:3] op_sel_hi:[1,0] neg_lo:[0,1] neg_hi:[0,1]
	v_sub_f32_e32 v127, v127, v2
	v_sub_f32_e32 v126, v126, v2
	v_sub_f32_e32 v125, v125, v2
	v_sub_f32_e32 v124, v124, v2
	v_sub_f32_e32 v123, v123, v2
	v_sub_f32_e32 v122, v122, v2
	v_sub_f32_e32 v121, v121, v2
	v_sub_f32_e32 v120, v120, v2
	v_sub_f32_e32 v119, v119, v2
	v_sub_f32_e32 v118, v118, v2
	v_sub_f32_e32 v117, v117, v2
	v_sub_f32_e32 v116, v116, v2
	v_sub_f32_e32 v115, v115, v2
	v_sub_f32_e32 v114, v114, v2
	v_sub_f32_e32 v113, v113, v2
	v_sub_f32_e32 v112, v112, v2
	v_mov_b32_e32 v81, v80
	v_mov_b32_e32 v82, v80
	v_mov_b32_e32 v83, v80
	v_mov_b32_e32 v84, v80
	v_mov_b32_e32 v85, v80
	v_mov_b32_e32 v86, v80
	v_mov_b32_e32 v87, v80
	v_mov_b32_e32 v88, v80
	v_mov_b32_e32 v89, v80
	v_mov_b32_e32 v90, v80
	v_mov_b32_e32 v91, v80
	v_mov_b32_e32 v92, v80
	v_mov_b32_e32 v93, v80
	v_mov_b32_e32 v94, v80
	v_mov_b32_e32 v95, v80
	v_mov_b32_e32 v96, v80
	v_mov_b32_e32 v97, v80
	v_mov_b32_e32 v98, v80
	v_mov_b32_e32 v99, v80
	v_mov_b32_e32 v100, v80
	v_mov_b32_e32 v101, v80
	v_mov_b32_e32 v102, v80
	v_mov_b32_e32 v103, v80
	v_mov_b32_e32 v104, v80
	v_mov_b32_e32 v105, v80
	v_mov_b32_e32 v106, v80
	v_mov_b32_e32 v107, v80
	v_mov_b32_e32 v108, v80
	v_mov_b32_e32 v109, v80
	v_mov_b32_e32 v110, v80
	v_mov_b32_e32 v111, v80
	v_cmp_gt_f32_e32 vcc, 1.0, v0
	s_cbranch_vccnz .LBB0_595
	s_branch .LBB0_598
.LBB0_607:
	v_mov_b32_e32 v4, v3
	s_nop 1
	v_permlane32_swap_b32_e32 v3, v4
	v_max_f32_e32 v3, v3, v4
	v_max_f32_e32 v2, v3, v3
	v_max_f32_e32 v4, 0, v2
	v_exp_f32_e64 v2, -v4
	v_add_f32_e32 v215, v215, v4
	v_xor_b32_e32 v80, 0x80000000, v215
	v_pk_add_f32 v[128:129], v[128:129], v[4:5] op_sel_hi:[1,0] neg_lo:[0,1] neg_hi:[0,1]
	v_pk_add_f32 v[130:131], v[130:131], v[4:5] op_sel_hi:[1,0] neg_lo:[0,1] neg_hi:[0,1]
	v_pk_add_f32 v[132:133], v[132:133], v[4:5] op_sel_hi:[1,0] neg_lo:[0,1] neg_hi:[0,1]
	v_pk_add_f32 v[134:135], v[134:135], v[4:5] op_sel_hi:[1,0] neg_lo:[0,1] neg_hi:[0,1]
	v_pk_add_f32 v[136:137], v[136:137], v[4:5] op_sel_hi:[1,0] neg_lo:[0,1] neg_hi:[0,1]
	v_pk_add_f32 v[138:139], v[138:139], v[4:5] op_sel_hi:[1,0] neg_lo:[0,1] neg_hi:[0,1]
	v_pk_add_f32 v[140:141], v[140:141], v[4:5] op_sel_hi:[1,0] neg_lo:[0,1] neg_hi:[0,1]
	v_pk_add_f32 v[142:143], v[142:143], v[4:5] op_sel_hi:[1,0] neg_lo:[0,1] neg_hi:[0,1]
	v_sub_f32_e32 v127, v127, v4
	v_sub_f32_e32 v126, v126, v4
	v_sub_f32_e32 v125, v125, v4
	v_sub_f32_e32 v124, v124, v4
	v_sub_f32_e32 v123, v123, v4
	v_sub_f32_e32 v122, v122, v4
	v_sub_f32_e32 v121, v121, v4
	v_sub_f32_e32 v120, v120, v4
	v_sub_f32_e32 v119, v119, v4
	v_sub_f32_e32 v118, v118, v4
	v_sub_f32_e32 v117, v117, v4
	v_sub_f32_e32 v116, v116, v4
	v_sub_f32_e32 v115, v115, v4
	v_sub_f32_e32 v114, v114, v4
	v_sub_f32_e32 v113, v113, v4
	v_sub_f32_e32 v112, v112, v4
	v_mov_b32_e32 v81, v80
	v_mov_b32_e32 v82, v80
	v_mov_b32_e32 v83, v80
	v_mov_b32_e32 v84, v80
	v_mov_b32_e32 v85, v80
	v_mov_b32_e32 v86, v80
	v_mov_b32_e32 v87, v80
	v_mov_b32_e32 v88, v80
	v_mov_b32_e32 v89, v80
	v_mov_b32_e32 v90, v80
	v_mov_b32_e32 v91, v80
	v_mov_b32_e32 v92, v80
	v_mov_b32_e32 v93, v80
	v_mov_b32_e32 v94, v80
	v_mov_b32_e32 v95, v80
	v_mov_b32_e32 v96, v80
	v_mov_b32_e32 v97, v80
	v_mov_b32_e32 v98, v80
	v_mov_b32_e32 v99, v80
	v_mov_b32_e32 v100, v80
	v_mov_b32_e32 v101, v80
	v_mov_b32_e32 v102, v80
	v_mov_b32_e32 v103, v80
	v_mov_b32_e32 v104, v80
	v_mov_b32_e32 v105, v80
	v_mov_b32_e32 v106, v80
	v_mov_b32_e32 v107, v80
	v_mov_b32_e32 v108, v80
	v_mov_b32_e32 v109, v80
	v_mov_b32_e32 v110, v80
	v_mov_b32_e32 v111, v80
	v_cmp_gt_f32_e32 vcc, 1.0, v2
	s_cbranch_vccnz .LBB0_604
	s_branch .LBB0_590
